# speedup vs baseline: 1.0286x; 1.0013x over previous
; #define K_LOAD(kt) do { sk0 = *(const bf16x8*)(kg + (size_t)(kt) * 8192); sk1 = *(const bf16x8*)(kg + (size_t)(kt) * 8192 + 4096); } while (0)
; #define V_LOAD(kt) do { sv0 = *(const bf16x8*)(vg + (size_t)(kt) * 8192); sv1 = *(const bf16x8*)(vg + (size_t)(kt) * 8192 + 4096); } while (0)
; #define K_STORE(bi) do { char* s_ = kbuf + (bi) * 16384; *(bf16x8*)(s_ + klds) = sk0; *(bf16x8*)(s_ + klds + 4096) = sk1; } while (0)
; #define V_STORE(bi) do { char* s_ = vbuf + (bi) * 16384 - 16384; \
;     s16x4 a0_ = {sv0[0], sv0[1], sv0[2], sv0[3]}, a1_ = {sv0[4], sv0[5], sv0[6], sv0[7]}; \
;     s16x4 b0_ = {sv1[0], sv1[1], sv1[2], sv1[3]}, b1_ = {sv1[4], sv1[5], sv1[6], sv1[7]}; \
;     *(s16x4*)(s_ + vlds0) = a0_; *(s16x4*)(s_ + vlds1) = a1_; *(s16x4*)(s_ + vlds0 + 8192) = b0_; *(s16x4*)(s_ + vlds1 + 8192) = b1_; } while (0)
; DEVI void attn_item(const Params& p, const int l, const int bh, const int qblk, const float lam, const float osc, char* smem) {
;     ...
;   bf16x8 qf[4];
;   {
;     const u16* qp = PBC + (tok0 + (size_t)qblk * 128 + qg * 32 + l31) * 1280 + 512 + h * 128 + m * 64 + hi * 8;
; #pragma unroll
;     for (int d0 = 0; d0 < 4; ++d0) qf[d0] = *(const bf16x8*)(qp + d0 * 16);
;   }
;   const int kkey = tid >> 4, kch = tid & 15;
;   const u16* kg = KT + kkey * 128 + kch * 8;
;   const int klds = (kch >> 3) * 8192 + swz(kkey, kch & 7);
;   const int ve = tid >> 3, vj = tid & 7;
;   const u16* vg = VT + ve * 64 + vj * 8;
;   const int vx = (ve >> 1) & 7;
;   const int vlds0 = 16384 + ve * 128 + ((((vj >> 1) * 2 + 0) ^ vx) << 4) + (vj & 1) * 8;
;   const int vlds1 = 16384 + ve * 128 + ((((vj >> 1) * 2 + 1) ^ vx) << 4) + (vj & 1) * 8;
;   bf16x8 sk0, sk1, sv0, sv1;
;   char* kbuf = stg; char* vbuf = stg + 32768;
;     ...
;   f32x16 o[4];
; #pragma unroll
;   for (int d0 = 0; d0 < 4; ++d0)
; #pragma unroll
;     for (int r = 0; r < 16; ++r) o[d0][r] = 0.f;
;   float m_reg = -1e30f, l_reg = 0.f;
;   const int xq = (l31 >> 1) & 7;
;   f32x16 pA0, pA1, pB0, pB1;
;   K_LOAD(0); V_LOAD(0);
;   {
;     const bf16x8 tk0 = *(const bf16x8*)(kg + (size_t)8192), tk1 = *(const bf16x8*)(kg + (size_t)8192 + 4096);
;     K_STORE(0); V_STORE(0);
;     sk0 = tk0; sk1 = tk1; K_STORE(1);
;   }
;   __syncthreads();
;   QK_TILE(pA0, pA1, 0);
;   __syncthreads();
.LBB0_537:
	s_or_b64 exec, exec, s[8:9]
	s_waitcnt lgkmcnt(0)
	s_barrier
	ds_read_b32 v2, v173
	s_movk_i32 s8, 0xbf
	s_waitcnt lgkmcnt(0)
	s_barrier
	v_cmp_lt_i32_e32 vcc, s8, v2
	v_readfirstlane_b32 s52, v2
	s_mov_b64 s[8:9], -1
	s_cbranch_vccnz .LBB0_532
	s_lshl_b32 s9, s52, 1
	s_or_b32 s9, s9, s87
	s_sub_i32 s8, 0x7f, s52
	s_sub_i32 s9, 0x17f, s9
	s_cmpk_lt_i32 s52, 0x80
	s_cselect_b32 s72, s8, s9
	s_cselect_b32 s52, s79, s86
	s_lshl_b32 s88, s72, 1
	s_cmp_gt_u32 s52, 5
	s_cselect_b32 s53, 0x4000, 0
	s_lshl_b64 s[8:9], s[72:73], 7
	s_add_u32 s84, s8, s53
	s_addc_u32 s85, s9, 0
	s_lshl_b32 s8, s52, 7
	s_add_i32 s9, s8, 0xfffffd00
	s_cmp_lt_u32 s52, 6
	s_cselect_b32 s72, s8, s9
	s_lshl_b32 s8, s52, 22
	s_mov_b32 s9, s73
	v_lshl_add_u64 v[20:21], v[174:175], 0, s[8:9]
	v_add_co_u32_e32 v12, vcc, s35, v20
	v_lshl_add_u64 v[10:11], v[176:177], 0, s[8:9]
	s_nop 0
	v_addc_co_u32_e32 v13, vcc, 0, v21, vcc
	v_add_co_u32_e32 v14, vcc, s35, v10
	s_movk_i32 s9, 0x4000
	s_nop 0
	v_addc_co_u32_e32 v15, vcc, 0, v11, vcc
	v_add_co_u32_e32 v22, vcc, s9, v20
	s_movk_i32 s9, 0x6000
	s_nop 0
	v_addc_co_u32_e32 v23, vcc, 0, v21, vcc
	v_or_b32_e32 v24, s84, v170
	v_mov_b64_e32 v[18:19], s[28:29]
	global_load_dwordx4 v[2:5], v[20:21], off
	global_load_dwordx4 v[6:9], v[10:11], off
	v_add_co_u32_e32 v20, vcc, s9, v20
	s_movk_i32 s9, 0xa00
	v_mad_u64_u32 v[18:19], s[52:53], v24, s9, v[18:19]
	v_mad_u32_u24 v19, s85, v211, v19
	global_load_dwordx4 v[10:13], v[12:13], off
	s_nop 0
	global_load_dwordx4 v[14:17], v[14:15], off
	v_addc_co_u32_e32 v21, vcc, 0, v21, vcc
	global_load_dwordx4 v[146:149], v[22:23], off
	global_load_dwordx4 v[150:153], v[20:21], off
	v_lshl_add_u64 v[18:19], s[72:73], 1, v[18:19]
	v_mov_b32_e32 v185, v173
	v_lshl_add_u64 v[18:19], v[18:19], 0, v[184:185]
	v_mov_b32_e32 v187, v173
	v_lshl_add_u64 v[18:19], v[18:19], 0, v[186:187]
	s_mov_b32 s9, 0x1da00000
	v_add_co_u32_e32 v20, vcc, s9, v18
	s_mov_b64 s[52:53], 0x1da00400
	s_nop 0
	v_addc_co_u32_e32 v21, vcc, 0, v19, vcc
	global_load_dwordx4 v[130:133], v[20:21], off offset:1024
	v_lshl_add_u64 v[18:19], v[18:19], 0, s[52:53]
	global_load_dwordx4 v[134:137], v[18:19], off offset:32
	global_load_dwordx4 v[138:141], v[18:19], off offset:64
	global_load_dwordx4 v[142:145], v[18:19], off offset:96
	v_add_u32_e32 v185, v201, v202
	v_add_u32_e32 v187, v201, v203
	v_add_u32_e32 v215, v201, v204
	v_add_u32_e32 v216, v201, v205
	s_mov_b32 s52, 0
	s_mov_b32 s53, s52
	s_mov_b32 s54, s52
	s_mov_b32 s55, s52
	s_mov_b32 s56, s52
	s_mov_b32 s57, s52
	s_mov_b32 s58, s52
	s_mov_b32 s59, s52
	s_mov_b32 s60, s52
	s_mov_b32 s61, s52
	s_mov_b32 s62, s52
	s_mov_b32 s63, s52
	s_mov_b32 s64, s52
	s_mov_b32 s65, s52
	s_mov_b32 s66, s52
	s_mov_b32 s67, s52
	v_mov_b64_e32 v[50:51], s[52:53]
	v_mov_b64_e32 v[52:53], s[54:55]
	v_mov_b64_e32 v[54:55], s[56:57]
	v_mov_b64_e32 v[56:57], s[58:59]
	v_mov_b64_e32 v[58:59], s[60:61]
	v_mov_b64_e32 v[60:61], s[62:63]
	v_mov_b64_e32 v[62:63], s[64:65]
	v_mov_b64_e32 v[64:65], s[66:67]
	s_add_i32 s53, s88, 2
	s_add_u32 s54, s28, s8
	v_mov_b64_e32 v[34:35], v[50:51]
	v_mov_b64_e32 v[18:19], v[50:51]
	v_add_u32_e32 v217, s88, v197
	s_addc_u32 s55, s29, 0
	s_add_u32 s54, s54, 0x22a08000
	s_addc_u32 s55, s55, 0
	v_mov_b32_e32 v218, 0
	v_mov_b32_e32 v192, 0xf149f2ca
	v_mov_b64_e32 v[36:37], v[52:53]
	v_mov_b64_e32 v[38:39], v[54:55]
	v_mov_b64_e32 v[40:41], v[56:57]
	s_waitcnt vmcnt(9)
	ds_write_b128 v212, v[2:5] offset:2048
	s_waitcnt vmcnt(8)
	ds_write_b128 v253, v[6:9] offset:34816
	s_waitcnt vmcnt(7)
	ds_write_b128 v212, v[10:13] offset:6144
	s_waitcnt vmcnt(6)
	ds_write_b128 v253, v[14:17] offset:43008
	s_waitcnt vmcnt(5)
	ds_write_b128 v212, v[146:149] offset:18432
	s_waitcnt vmcnt(4)
	ds_write_b128 v212, v[150:153] offset:22528
	s_waitcnt lgkmcnt(0)
	s_barrier
	ds_read_b128 v[2:5], v185 offset:2048
	ds_read_b128 v[6:9], v185 offset:6144
	s_waitcnt vmcnt(3) lgkmcnt(1)
	v_mfma_f32_32x32x16_bf16 v[66:81], v[2:5], v[130:133], 0
	v_mov_b64_e32 v[42:43], v[58:59]
	v_mov_b64_e32 v[44:45], v[60:61]
	v_mov_b64_e32 v[46:47], v[62:63]
	v_mov_b64_e32 v[48:49], v[64:65]
	v_mov_b64_e32 v[20:21], v[52:53]
	v_mov_b64_e32 v[22:23], v[54:55]
	v_mov_b64_e32 v[24:25], v[56:57]
	s_waitcnt lgkmcnt(0)
	v_mfma_f32_32x32x16_bf16 v[82:97], v[6:9], v[130:133], 0
	ds_read_b128 v[2:5], v187 offset:2048
	ds_read_b128 v[6:9], v187 offset:6144
	v_mov_b64_e32 v[26:27], v[58:59]
	v_mov_b64_e32 v[28:29], v[60:61]
	v_mov_b64_e32 v[30:31], v[62:63]
	v_mov_b64_e32 v[32:33], v[64:65]
	s_waitcnt vmcnt(2) lgkmcnt(1)
	v_mfma_f32_32x32x16_bf16 v[66:81], v[2:5], v[134:137], v[66:81]
	ds_read_b128 v[2:5], v215 offset:2048
	s_waitcnt lgkmcnt(1)
	v_mfma_f32_32x32x16_bf16 v[82:97], v[6:9], v[134:137], v[82:97]
	ds_read_b128 v[6:9], v215 offset:6144
	s_waitcnt vmcnt(1) lgkmcnt(1)
	v_mfma_f32_32x32x16_bf16 v[66:81], v[2:5], v[138:141], v[66:81]
	ds_read_b128 v[2:5], v216 offset:2048
	s_waitcnt lgkmcnt(1)
	v_mfma_f32_32x32x16_bf16 v[82:97], v[6:9], v[138:141], v[82:97]
	ds_read_b128 v[6:9], v216 offset:6144
	s_waitcnt lgkmcnt(0)
	s_barrier
	s_waitcnt vmcnt(0)
	v_mfma_f32_32x32x16_bf16 v[66:81], v[2:5], v[142:145], v[66:81]
	v_mfma_f32_32x32x16_bf16 v[82:97], v[6:9], v[142:145], v[82:97]
	v_mov_b64_e32 v[2:3], v[50:51]
	v_mov_b64_e32 v[4:5], v[52:53]
	v_mov_b64_e32 v[6:7], v[54:55]
	v_mov_b64_e32 v[8:9], v[56:57]
	v_mov_b64_e32 v[10:11], v[58:59]
	v_mov_b64_e32 v[12:13], v[60:61]
	v_mov_b64_e32 v[14:15], v[62:63]
	v_mov_b64_e32 v[16:17], v[64:65]
	s_nop 15
	s_nop 15
	v_max_f32_e32 v247, v67, v67
	v_max_f32_e32 v248, v66, v66
	v_max_f32_e32 v247, v248, v247
	v_max3_f32 v247, v247, v68, v69
	v_max3_f32 v247, v247, v70, v71
	v_max3_f32 v247, v247, v72, v73
	v_max3_f32 v247, v247, v74, v75
	v_max3_f32 v247, v247, v76, v77
	v_max3_f32 v247, v247, v78, v79
	v_max3_f32 v249, v247, v80, v81
	v_max3_f32 v249, v249, v82, v83
	v_max3_f32 v249, v249, v84, v85
	v_max3_f32 v249, v249, v86, v87
	v_max3_f32 v249, v249, v88, v89
	v_max3_f32 v249, v249, v90, v91
	v_max3_f32 v249, v249, v92, v93
	v_max3_f32 v249, v249, v94, v95
	v_max3_f32 v249, v249, v96, v97
	s_branch .LBB0_540

.LBB0_542:
	s_add_u32 m0, s101, 0xc810
	s_nop 0
	global_load_lds_dwordx4 v243, s[54:55]
	s_add_u32 m0, s101, 0xe810
	s_nop 0
	global_load_lds_dwordx4 v244, s[54:55]
	v_cmp_le_u32_e32 vcc, s52, v217
	s_and_saveexec_b64 s[8:9], vcc
	s_cbranch_execz .LBB0_548
	s_waitcnt lgkmcnt(1)
	v_mfma_f32_32x32x16_bf16 v[98:113], v[98:101], v[130:133], 0
	ds_read_b128 v[118:121], v187 offset:18432
	ds_read_b128 v[220:223], v187 offset:22528
	s_waitcnt lgkmcnt(1)
	v_mfma_f32_32x32x16_bf16 v[98:113], v[118:121], v[134:137], v[98:113]
	ds_read_b128 v[118:121], v215 offset:18432
	s_waitcnt lgkmcnt(0)
	v_mfma_f32_32x32x16_bf16 v[98:113], v[118:121], v[138:141], v[98:113]
	ds_read_b128 v[118:121], v216 offset:18432
	s_waitcnt lgkmcnt(0)
	v_mfma_f32_32x32x16_bf16 v[98:113], v[118:121], v[142:145], v[98:113]
	v_mfma_f32_32x32x16_bf16 v[114:129], v[114:117], v[130:133], 0
	v_mfma_f32_32x32x16_bf16 v[114:129], v[220:223], v[134:137], v[114:129]
	v_mov_b32_e32 v219, v249
	v_mov_b32_e32 v220, v249
	s_nop 1
	v_permlane32_swap_b32_e32 v219, v220
	v_max_f32_e32 v220, v220, v220
	v_max_f32_e32 v219, v219, v219
	v_max_f32_e32 v219, v219, v220
	v_sub_f32_e32 v220, v219, v192
	v_cmp_ge_f32_e32 vcc, s36, v220
	s_cmp_eq_u64 vcc, exec
	v_max_f32_e32 v220, v192, v192
	s_cselect_b64 vcc, -1, 0
	v_max_f32_e32 v219, v220, v219
	v_cndmask_b32_e32 v219, v219, v192, vcc
	v_sub_f32_e32 v192, v192, v219
	v_mul_f32_e32 v192, 0x3e38aa3b, v192
	v_exp_f32_e32 v220, v192
	v_mul_f32_e32 v192, 0xbe38aa3b, v219
	v_pk_fma_f32 v[96:97], v[96:97], s[78:79], v[192:193] op_sel_hi:[1,0,0]
	ds_read_b128 v[224:227], v215 offset:22528
	v_pk_fma_f32 v[86:87], v[86:87], s[78:79], v[192:193] op_sel_hi:[1,0,0]
	v_pk_fma_f32 v[88:89], v[88:89], s[78:79], v[192:193] op_sel_hi:[1,0,0]
	v_pk_fma_f32 v[90:91], v[90:91], s[78:79], v[192:193] op_sel_hi:[1,0,0]
	v_pk_fma_f32 v[92:93], v[92:93], s[78:79], v[192:193] op_sel_hi:[1,0,0]
	v_pk_fma_f32 v[94:95], v[94:95], s[78:79], v[192:193] op_sel_hi:[1,0,0]
	ds_read_b128 v[162:165], v216 offset:22528
	v_pk_fma_f32 v[84:85], v[84:85], s[78:79], v[192:193] op_sel_hi:[1,0,0]
	s_waitcnt lgkmcnt(1)
	v_mfma_f32_32x32x16_bf16 v[114:129], v[224:227], v[138:141], v[114:129]
	v_fma_f32 v66, v66, s78, v192
	v_fma_f32 v67, v67, s78, v192
	v_fma_f32 v68, v68, s78, v192
	v_fma_f32 v69, v69, s78, v192
	v_exp_f32_e32 v66, v66
	v_exp_f32_e32 v67, v67
	v_exp_f32_e32 v68, v68
	v_exp_f32_e32 v69, v69
	v_pk_fma_f32 v[70:71], v[70:71], s[78:79], v[192:193] op_sel_hi:[1,0,0]
	v_pk_add_f32 v[222:223], v[66:67], 0 op_sel_hi:[1,0]
	v_exp_f32_e32 v70, v70
	v_exp_f32_e32 v71, v71
	v_pk_add_f32 v[222:223], v[68:69], v[222:223]
	v_pk_fma_f32 v[72:73], v[72:73], s[78:79], v[192:193] op_sel_hi:[1,0,0]
	v_exp_f32_e32 v84, v84
	v_pk_add_f32 v[222:223], v[70:71], v[222:223]
	v_exp_f32_e32 v72, v72
	v_exp_f32_e32 v73, v73
	s_waitcnt lgkmcnt(0)
	v_mfma_f32_32x32x16_bf16 v[114:129], v[162:165], v[142:145], v[114:129]
	v_fma_f32 v74, v74, s78, v192
	v_fma_f32 v75, v75, s78, v192
	v_fma_f32 v76, v76, s78, v192
	v_fma_f32 v77, v77, s78, v192
	v_exp_f32_e32 v74, v74
	v_exp_f32_e32 v75, v75
	v_exp_f32_e32 v76, v76
	v_exp_f32_e32 v77, v77
	v_pk_fma_f32 v[78:79], v[78:79], s[78:79], v[192:193] op_sel_hi:[1,0,0]
	v_pk_fma_f32 v[80:81], v[80:81], s[78:79], v[192:193] op_sel_hi:[1,0,0]
	v_exp_f32_e32 v78, v78
	v_exp_f32_e32 v79, v79
	v_pk_add_f32 v[222:223], v[72:73], v[222:223]
	v_exp_f32_e32 v80, v80
	v_exp_f32_e32 v81, v81
	v_pk_fma_f32 v[82:83], v[82:83], s[78:79], v[192:193] op_sel_hi:[1,0,0]
	v_pk_add_f32 v[222:223], v[74:75], v[222:223]
	v_exp_f32_e32 v82, v82
	v_exp_f32_e32 v83, v83
	v_pk_add_f32 v[222:223], v[76:77], v[222:223]
	v_exp_f32_e32 v85, v85
	v_pk_add_f32 v[222:223], v[78:79], v[222:223]
	v_exp_f32_e32 v86, v86
	v_exp_f32_e32 v87, v87
	v_pk_add_f32 v[222:223], v[80:81], v[222:223]
	v_exp_f32_e32 v88, v88
	v_exp_f32_e32 v89, v89
	v_pk_add_f32 v[162:163], v[82:83], v[222:223]
	v_exp_f32_e32 v90, v90
	v_exp_f32_e32 v91, v91
	v_pk_add_f32 v[162:163], v[84:85], v[162:163]
	v_exp_f32_e32 v92, v92
	v_exp_f32_e32 v93, v93
	v_pk_add_f32 v[162:163], v[86:87], v[162:163]
	v_exp_f32_e32 v94, v94
	v_exp_f32_e32 v95, v95
	v_pk_add_f32 v[162:163], v[88:89], v[162:163]
	v_exp_f32_e32 v96, v96
	v_exp_f32_e32 v97, v97
	v_pk_add_f32 v[162:163], v[90:91], v[162:163]
	s_nop 0
	v_pk_add_f32 v[162:163], v[92:93], v[162:163]
	s_nop 0
	v_pk_add_f32 v[162:163], v[94:95], v[162:163]
	s_nop 0
	v_pk_add_f32 v[162:163], v[96:97], v[162:163]
	s_nop 0
	v_pk_add_f32 v[162:163], v[162:163], v[162:163] op_sel:[0,1] op_sel_hi:[1,0]
	s_nop 0
	v_mov_b32_e32 v163, v162
	s_nop 1
	v_permlane32_swap_b32_e32 v162, v163
	s_cbranch_vccnz .LBB0_547
	s_waitcnt lgkmcnt(0)
	s_and_saveexec_b64 s[60:61], s[2:3]
	ds_write_b32 v207, v220
	s_or_b64 exec, exec, s[60:61]
	s_waitcnt lgkmcnt(0)
	v_add_u32_e32 v164, v206, v194
	ds_read_b128 v[222:225], v164 offset:96
	ds_read_b128 v[226:229], v164 offset:64
	ds_read_b128 v[230:233], v164 offset:32
	ds_read_b128 v[234:237], v164
	s_waitcnt lgkmcnt(0)
	s_waitcnt lgkmcnt(3)
	v_pk_mul_f32 v[62:63], v[62:63], v[222:223]
	s_waitcnt lgkmcnt(2)
	v_pk_mul_f32 v[58:59], v[58:59], v[226:227]
	s_waitcnt lgkmcnt(1)
	v_pk_mul_f32 v[54:55], v[54:55], v[230:231]
	v_pk_mul_f32 v[64:65], v[64:65], v[224:225]
	v_pk_mul_f32 v[60:61], v[60:61], v[228:229]
	v_pk_mul_f32 v[56:57], v[56:57], v[232:233]
	s_waitcnt lgkmcnt(0)
	v_pk_mul_f32 v[52:53], v[52:53], v[236:237]
	v_pk_mul_f32 v[50:51], v[50:51], v[234:235]
	v_pk_mul_f32 v[46:47], v[46:47], v[222:223]
	v_pk_mul_f32 v[42:43], v[42:43], v[226:227]
	v_pk_mul_f32 v[38:39], v[38:39], v[230:231]
	v_pk_mul_f32 v[48:49], v[48:49], v[224:225]
	v_pk_mul_f32 v[44:45], v[44:45], v[228:229]
	v_pk_mul_f32 v[40:41], v[40:41], v[232:233]
	v_pk_mul_f32 v[36:37], v[36:37], v[236:237]
	v_pk_mul_f32 v[34:35], v[34:35], v[234:235]
	v_pk_mul_f32 v[30:31], v[30:31], v[222:223]
	v_pk_mul_f32 v[26:27], v[26:27], v[226:227]
	v_pk_mul_f32 v[22:23], v[22:23], v[230:231]
	v_pk_mul_f32 v[32:33], v[32:33], v[224:225]
	v_pk_mul_f32 v[28:29], v[28:29], v[228:229]
	v_pk_mul_f32 v[24:25], v[24:25], v[232:233]
	v_pk_mul_f32 v[20:21], v[20:21], v[236:237]
	v_pk_mul_f32 v[18:19], v[18:19], v[234:235]
	v_pk_mul_f32 v[14:15], v[14:15], v[222:223]
	v_pk_mul_f32 v[10:11], v[10:11], v[226:227]
	v_pk_mul_f32 v[6:7], v[6:7], v[230:231]
	v_pk_mul_f32 v[16:17], v[16:17], v[224:225]
	v_pk_mul_f32 v[12:13], v[12:13], v[228:229]
	v_pk_mul_f32 v[8:9], v[8:9], v[232:233]
	v_pk_mul_f32 v[4:5], v[4:5], v[236:237]
	v_pk_mul_f32 v[2:3], v[2:3], v[234:235]
.LBB0_547:
	v_add_u32_e32 v164, v200, v202
	ds_read_b128 v[226:229], v164 offset:34816
	ds_read_b128 v[230:233], v164 offset:38912
	ds_read_b128 v[234:237], v164 offset:43008
	ds_read_b128 v[238:241], v164 offset:47104
	v_add_u32_e32 v164, v200, v203
	v_cvt_pk_bf16_f32 v222, v66, v67
	v_cvt_pk_bf16_f32 v223, v68, v69
	v_cvt_pk_bf16_f32 v224, v70, v71
	v_cvt_pk_bf16_f32 v225, v72, v73
	v_add_f32_e32 v162, v162, v163
	s_waitcnt lgkmcnt(3)
	v_mfma_f32_32x32x16_bf16 v[50:65], v[222:225], v[226:229], v[50:65]
	ds_read_b128 v[226:229], v164 offset:34816
	v_max_f32_e32 v247, v99, v99
	v_max_f32_e32 v248, v98, v98
	v_mov_b32_e32 v192, v219
	s_waitcnt lgkmcnt(3)
	v_mfma_f32_32x32x16_bf16 v[34:49], v[222:225], v[230:233], v[34:49]
	ds_read_b128 v[230:233], v164 offset:38912
	v_max_f32_e32 v247, v248, v247
	v_max3_f32 v247, v247, v100, v101
	s_waitcnt lgkmcnt(3)
	v_mfma_f32_32x32x16_bf16 v[18:33], v[222:225], v[234:237], v[18:33]
	ds_read_b128 v[234:237], v164 offset:43008
	v_max3_f32 v247, v247, v102, v103
	v_max3_f32 v247, v247, v104, v105
	s_waitcnt lgkmcnt(3)
	v_mfma_f32_32x32x16_bf16 v[2:17], v[222:225], v[238:241], v[2:17]
	ds_read_b128 v[238:241], v164 offset:47104
	v_max3_f32 v247, v247, v106, v107
	v_max3_f32 v247, v247, v108, v109
	v_add_u32_e32 v164, v200, v204
	v_cvt_pk_bf16_f32 v222, v74, v75
	v_cvt_pk_bf16_f32 v223, v76, v77
	v_cvt_pk_bf16_f32 v224, v78, v79
	v_cvt_pk_bf16_f32 v225, v80, v81
	s_waitcnt lgkmcnt(3)
	v_mfma_f32_32x32x16_bf16 v[50:65], v[222:225], v[226:229], v[50:65]
	ds_read_b128 v[226:229], v164 offset:34816
	v_max3_f32 v247, v247, v110, v111
	v_max3_f32 v254, v247, v112, v113
	s_waitcnt lgkmcnt(3)
	v_mfma_f32_32x32x16_bf16 v[34:49], v[222:225], v[230:233], v[34:49]
	ds_read_b128 v[230:233], v164 offset:38912
	v_max3_f32 v250, v254, v114, v115
	v_max3_f32 v250, v250, v116, v117
	s_waitcnt lgkmcnt(3)
	v_mfma_f32_32x32x16_bf16 v[18:33], v[222:225], v[234:237], v[18:33]
	ds_read_b128 v[234:237], v164 offset:43008
	v_max3_f32 v250, v250, v118, v119
	v_max3_f32 v250, v250, v120, v121
	s_waitcnt lgkmcnt(3)
	v_mfma_f32_32x32x16_bf16 v[2:17], v[222:225], v[238:241], v[2:17]
	ds_read_b128 v[238:241], v164 offset:47104
	v_max3_f32 v250, v250, v122, v123
	v_max3_f32 v250, v250, v124, v125
	v_add_u32_e32 v164, v200, v205
	v_cvt_pk_bf16_f32 v222, v82, v83
	v_cvt_pk_bf16_f32 v223, v84, v85
	v_cvt_pk_bf16_f32 v224, v86, v87
	v_cvt_pk_bf16_f32 v225, v88, v89
	s_waitcnt lgkmcnt(3)
	v_mfma_f32_32x32x16_bf16 v[50:65], v[222:225], v[226:229], v[50:65]
	ds_read_b128 v[226:229], v164 offset:34816
	v_max3_f32 v250, v250, v126, v127
	v_max3_f32 v250, v250, v128, v129
	s_waitcnt lgkmcnt(3)
	v_mfma_f32_32x32x16_bf16 v[34:49], v[222:225], v[230:233], v[34:49]
	ds_read_b128 v[230:233], v164 offset:38912
	s_waitcnt lgkmcnt(3)
	v_mfma_f32_32x32x16_bf16 v[18:33], v[222:225], v[234:237], v[18:33]
	ds_read_b128 v[234:237], v164 offset:43008
	s_waitcnt lgkmcnt(3)
	v_mfma_f32_32x32x16_bf16 v[2:17], v[222:225], v[238:241], v[2:17]
	ds_read_b128 v[238:241], v164 offset:47104
	v_cvt_pk_bf16_f32 v222, v90, v91
	v_cvt_pk_bf16_f32 v223, v92, v93
	v_cvt_pk_bf16_f32 v224, v94, v95
	v_cvt_pk_bf16_f32 v225, v96, v97
	v_cndmask_b32_e64 v164, v220, 1.0, vcc
	v_fmac_f32_e32 v162, v218, v164
	s_waitcnt lgkmcnt(3)
	v_mfma_f32_32x32x16_bf16 v[50:65], v[222:225], v[226:229], v[50:65]
	v_mov_b32_e32 v218, v162
	s_waitcnt lgkmcnt(2)
	v_mfma_f32_32x32x16_bf16 v[34:49], v[222:225], v[230:233], v[34:49]
	s_waitcnt lgkmcnt(1)
	v_mfma_f32_32x32x16_bf16 v[18:33], v[222:225], v[234:237], v[18:33]
	s_waitcnt lgkmcnt(0)
	v_mfma_f32_32x32x16_bf16 v[2:17], v[222:225], v[238:241], v[2:17]

.LBB0_557:
	s_waitcnt lgkmcnt(1)
	v_mfma_f32_32x32x16_bf16 v[66:81], v[66:69], v[130:133], 0
	ds_read_b128 v[86:89], v187 offset:2048
	ds_read_b128 v[188:191], v187 offset:6144
	s_waitcnt lgkmcnt(1)
	v_mfma_f32_32x32x16_bf16 v[66:81], v[86:89], v[134:137], v[66:81]
	ds_read_b128 v[86:89], v215 offset:2048
	s_waitcnt lgkmcnt(0)
	v_mfma_f32_32x32x16_bf16 v[66:81], v[86:89], v[138:141], v[66:81]
	ds_read_b128 v[86:89], v216 offset:2048
	s_waitcnt lgkmcnt(0)
	v_mfma_f32_32x32x16_bf16 v[66:81], v[86:89], v[142:145], v[66:81]
	v_mfma_f32_32x32x16_bf16 v[82:97], v[82:85], v[130:133], 0
	v_mfma_f32_32x32x16_bf16 v[82:97], v[188:191], v[134:137], v[82:97]
	v_mov_b32_e32 v188, v250
	v_mov_b32_e32 v189, v250
	s_nop 1
	v_permlane32_swap_b32_e32 v188, v189
	v_max_f32_e32 v189, v189, v189
	v_max_f32_e32 v188, v188, v188
	v_max_f32_e32 v188, v188, v189
	v_sub_f32_e32 v189, v188, v192
	v_cmp_ge_f32_e32 vcc, s36, v189
	s_cmp_eq_u64 vcc, exec
	v_max_f32_e32 v189, v192, v192
	s_cselect_b64 vcc, -1, 0
	v_max_f32_e32 v188, v189, v188
	v_cndmask_b32_e32 v189, v188, v192, vcc
	v_sub_f32_e32 v188, v192, v189
	v_mul_f32_e32 v188, 0x3e38aa3b, v188
	v_exp_f32_e32 v190, v188
	v_mul_f32_e32 v188, 0xbe38aa3b, v189
	v_pk_fma_f32 v[128:129], v[128:129], s[78:79], v[188:189] op_sel_hi:[1,0,0]
	ds_read_b128 v[220:223], v215 offset:6144
	v_pk_fma_f32 v[118:119], v[118:119], s[78:79], v[188:189] op_sel_hi:[1,0,0]
	v_pk_fma_f32 v[120:121], v[120:121], s[78:79], v[188:189] op_sel_hi:[1,0,0]
	v_pk_fma_f32 v[122:123], v[122:123], s[78:79], v[188:189] op_sel_hi:[1,0,0]
	v_pk_fma_f32 v[124:125], v[124:125], s[78:79], v[188:189] op_sel_hi:[1,0,0]
	v_pk_fma_f32 v[126:127], v[126:127], s[78:79], v[188:189] op_sel_hi:[1,0,0]
	ds_read_b128 v[162:165], v216 offset:6144
	v_pk_fma_f32 v[108:109], v[108:109], s[78:79], v[188:189] op_sel_hi:[1,0,0]
	v_pk_fma_f32 v[110:111], v[110:111], s[78:79], v[188:189] op_sel_hi:[1,0,0]
	v_pk_fma_f32 v[112:113], v[112:113], s[78:79], v[188:189] op_sel_hi:[1,0,0]
	v_pk_fma_f32 v[114:115], v[114:115], s[78:79], v[188:189] op_sel_hi:[1,0,0]
	v_pk_fma_f32 v[116:117], v[116:117], s[78:79], v[188:189] op_sel_hi:[1,0,0]
	s_waitcnt lgkmcnt(1)
	v_mfma_f32_32x32x16_bf16 v[82:97], v[220:223], v[138:141], v[82:97]
	v_fma_f32 v98, v98, s78, v188
	v_fma_f32 v99, v99, s78, v188
	v_fma_f32 v100, v100, s78, v188
	v_fma_f32 v101, v101, s78, v188
	v_exp_f32_e32 v98, v98
	v_exp_f32_e32 v99, v99
	v_exp_f32_e32 v100, v100
	v_exp_f32_e32 v101, v101
	v_pk_fma_f32 v[102:103], v[102:103], s[78:79], v[188:189] op_sel_hi:[1,0,0]
	v_pk_fma_f32 v[104:105], v[104:105], s[78:79], v[188:189] op_sel_hi:[1,0,0]
	v_exp_f32_e32 v102, v102
	v_exp_f32_e32 v103, v103
	v_exp_f32_e32 v104, v104
	v_exp_f32_e32 v105, v105
	v_pk_fma_f32 v[106:107], v[106:107], s[78:79], v[188:189] op_sel_hi:[1,0,0]
	v_pk_add_f32 v[220:221], v[98:99], 0 op_sel_hi:[1,0]
	v_exp_f32_e32 v106, v106
	v_exp_f32_e32 v107, v107
	v_pk_add_f32 v[220:221], v[100:101], v[220:221]
	v_exp_f32_e32 v108, v108
	v_exp_f32_e32 v109, v109
	v_pk_add_f32 v[220:221], v[102:103], v[220:221]
	v_exp_f32_e32 v110, v110
	v_exp_f32_e32 v111, v111
	v_pk_add_f32 v[220:221], v[104:105], v[220:221]
	v_exp_f32_e32 v112, v112
	v_exp_f32_e32 v113, v113
	v_pk_add_f32 v[220:221], v[106:107], v[220:221]
	v_exp_f32_e32 v114, v114
	v_exp_f32_e32 v115, v115
	v_pk_add_f32 v[220:221], v[108:109], v[220:221]
	v_exp_f32_e32 v116, v116
	v_exp_f32_e32 v117, v117
	v_pk_add_f32 v[220:221], v[110:111], v[220:221]
	v_exp_f32_e32 v118, v118
	v_exp_f32_e32 v119, v119
	v_pk_add_f32 v[220:221], v[112:113], v[220:221]
	v_exp_f32_e32 v120, v120
	v_exp_f32_e32 v121, v121
	s_waitcnt lgkmcnt(0)
	v_mfma_f32_32x32x16_bf16 v[82:97], v[162:165], v[142:145], v[82:97]
	v_add_f32_e64 v162, v114, v220
	v_add_f32_e64 v163, v115, v221
	v_exp_f32_e32 v122, v122
	v_exp_f32_e32 v123, v123
	v_pk_add_f32 v[162:163], v[116:117], v[162:163]
	v_exp_f32_e32 v124, v124
	v_exp_f32_e32 v125, v125
	v_pk_add_f32 v[162:163], v[118:119], v[162:163]
	v_exp_f32_e32 v126, v126
	v_exp_f32_e32 v127, v127
	v_pk_add_f32 v[162:163], v[120:121], v[162:163]
	v_exp_f32_e32 v128, v128
	v_exp_f32_e32 v129, v129
	v_pk_add_f32 v[162:163], v[122:123], v[162:163]
	s_nop 0
	v_pk_add_f32 v[162:163], v[124:125], v[162:163]
	s_nop 0
	v_pk_add_f32 v[162:163], v[126:127], v[162:163]
	s_nop 0
	v_pk_add_f32 v[162:163], v[128:129], v[162:163]
	s_nop 0
	v_pk_add_f32 v[162:163], v[162:163], v[162:163] op_sel:[0,1] op_sel_hi:[1,0]
	s_nop 0
	v_mov_b32_e32 v163, v162
	s_nop 1
	v_permlane32_swap_b32_e32 v162, v163
	s_cbranch_vccnz .LBB0_561
	s_waitcnt lgkmcnt(0)
	s_and_saveexec_b64 s[62:63], s[2:3]
	ds_write_b32 v207, v190
	s_or_b64 exec, exec, s[62:63]
	s_waitcnt lgkmcnt(0)
	v_add_u32_e32 v164, v206, v194
	ds_read_b128 v[220:223], v164 offset:96
	ds_read_b128 v[224:227], v164 offset:64
	ds_read_b128 v[228:231], v164 offset:32
	ds_read_b128 v[232:235], v164
	s_waitcnt lgkmcnt(0)
	s_waitcnt lgkmcnt(3)
	v_pk_mul_f32 v[62:63], v[62:63], v[220:221]
	s_waitcnt lgkmcnt(2)
	v_pk_mul_f32 v[58:59], v[58:59], v[224:225]
	s_waitcnt lgkmcnt(1)
	v_pk_mul_f32 v[54:55], v[54:55], v[228:229]
	v_pk_mul_f32 v[64:65], v[64:65], v[222:223]
	v_pk_mul_f32 v[60:61], v[60:61], v[226:227]
	v_pk_mul_f32 v[56:57], v[56:57], v[230:231]
	s_waitcnt lgkmcnt(0)
	v_pk_mul_f32 v[52:53], v[52:53], v[234:235]
	v_pk_mul_f32 v[50:51], v[50:51], v[232:233]
	v_pk_mul_f32 v[46:47], v[46:47], v[220:221]
	v_pk_mul_f32 v[42:43], v[42:43], v[224:225]
	v_pk_mul_f32 v[38:39], v[38:39], v[228:229]
	v_pk_mul_f32 v[48:49], v[48:49], v[222:223]
	v_pk_mul_f32 v[44:45], v[44:45], v[226:227]
	v_pk_mul_f32 v[40:41], v[40:41], v[230:231]
	v_pk_mul_f32 v[36:37], v[36:37], v[234:235]
	v_pk_mul_f32 v[34:35], v[34:35], v[232:233]
	v_pk_mul_f32 v[30:31], v[30:31], v[220:221]
	v_pk_mul_f32 v[26:27], v[26:27], v[224:225]
	v_pk_mul_f32 v[22:23], v[22:23], v[228:229]
	v_pk_mul_f32 v[32:33], v[32:33], v[222:223]
	v_pk_mul_f32 v[28:29], v[28:29], v[226:227]
	v_pk_mul_f32 v[24:25], v[24:25], v[230:231]
	v_pk_mul_f32 v[20:21], v[20:21], v[234:235]
	v_pk_mul_f32 v[18:19], v[18:19], v[232:233]
	v_pk_mul_f32 v[14:15], v[14:15], v[220:221]
	v_pk_mul_f32 v[10:11], v[10:11], v[224:225]
	v_pk_mul_f32 v[6:7], v[6:7], v[228:229]
	v_pk_mul_f32 v[16:17], v[16:17], v[222:223]
	v_pk_mul_f32 v[12:13], v[12:13], v[226:227]
	v_pk_mul_f32 v[8:9], v[8:9], v[230:231]
	v_pk_mul_f32 v[4:5], v[4:5], v[234:235]
	v_pk_mul_f32 v[2:3], v[2:3], v[232:233]
.LBB0_561:
	v_add_u32_e32 v164, v200, v202
	ds_read_b128 v[224:227], v164 offset:51200
	ds_read_b128 v[228:231], v164 offset:55296
	ds_read_b128 v[232:235], v164 offset:59392
	ds_read_b128 v[236:239], v164 offset:63488
	v_add_u32_e32 v164, v200, v203
	v_cvt_pk_bf16_f32 v220, v98, v99
	v_cvt_pk_bf16_f32 v221, v100, v101
	v_cvt_pk_bf16_f32 v222, v102, v103
	v_cvt_pk_bf16_f32 v223, v104, v105
	v_add_f32_e32 v162, v162, v163
	s_waitcnt lgkmcnt(3)
	v_mfma_f32_32x32x16_bf16 v[50:65], v[220:223], v[224:227], v[50:65]
	ds_read_b128 v[224:227], v164 offset:51200
	v_max_f32_e32 v247, v67, v67
	v_max_f32_e32 v248, v66, v66
	v_mov_b32_e32 v192, v189
	s_waitcnt lgkmcnt(3)
	v_mfma_f32_32x32x16_bf16 v[34:49], v[220:223], v[228:231], v[34:49]
	ds_read_b128 v[228:231], v164 offset:55296
	v_max_f32_e32 v247, v248, v247
	v_max3_f32 v247, v247, v68, v69
	s_waitcnt lgkmcnt(3)
	v_mfma_f32_32x32x16_bf16 v[18:33], v[220:223], v[232:235], v[18:33]
	ds_read_b128 v[232:235], v164 offset:59392
	v_max3_f32 v247, v247, v70, v71
	v_max3_f32 v247, v247, v72, v73
	s_waitcnt lgkmcnt(3)
	v_mfma_f32_32x32x16_bf16 v[2:17], v[220:223], v[236:239], v[2:17]
	ds_read_b128 v[236:239], v164 offset:63488
	v_max3_f32 v247, v247, v74, v75
	v_max3_f32 v247, v247, v76, v77
	v_add_u32_e32 v164, v200, v204
	v_cvt_pk_bf16_f32 v220, v106, v107
	v_cvt_pk_bf16_f32 v221, v108, v109
	v_cvt_pk_bf16_f32 v222, v110, v111
	v_cvt_pk_bf16_f32 v223, v112, v113
	s_waitcnt lgkmcnt(3)
	v_mfma_f32_32x32x16_bf16 v[50:65], v[220:223], v[224:227], v[50:65]
	ds_read_b128 v[224:227], v164 offset:51200
	v_max3_f32 v247, v247, v78, v79
	v_max3_f32 v249, v247, v80, v81
	s_waitcnt lgkmcnt(3)
	v_mfma_f32_32x32x16_bf16 v[34:49], v[220:223], v[228:231], v[34:49]
	ds_read_b128 v[228:231], v164 offset:55296
	v_max3_f32 v249, v249, v82, v83
	v_max3_f32 v249, v249, v84, v85
	s_waitcnt lgkmcnt(3)
	v_mfma_f32_32x32x16_bf16 v[18:33], v[220:223], v[232:235], v[18:33]
	ds_read_b128 v[232:235], v164 offset:59392
	v_max3_f32 v249, v249, v86, v87
	v_max3_f32 v249, v249, v88, v89
	s_waitcnt lgkmcnt(3)
	v_mfma_f32_32x32x16_bf16 v[2:17], v[220:223], v[236:239], v[2:17]
	ds_read_b128 v[236:239], v164 offset:63488
	v_max3_f32 v249, v249, v90, v91
	v_max3_f32 v249, v249, v92, v93
	v_add_u32_e32 v164, v200, v205
	v_cvt_pk_bf16_f32 v220, v114, v115
	v_cvt_pk_bf16_f32 v221, v116, v117
	v_cvt_pk_bf16_f32 v222, v118, v119
	v_cvt_pk_bf16_f32 v223, v120, v121
	s_waitcnt lgkmcnt(3)
	v_mfma_f32_32x32x16_bf16 v[50:65], v[220:223], v[224:227], v[50:65]
	ds_read_b128 v[224:227], v164 offset:51200
	v_max3_f32 v249, v249, v94, v95
	v_max3_f32 v249, v249, v96, v97
	s_waitcnt lgkmcnt(3)
	v_mfma_f32_32x32x16_bf16 v[34:49], v[220:223], v[228:231], v[34:49]
	ds_read_b128 v[228:231], v164 offset:55296
	s_waitcnt lgkmcnt(3)
	v_mfma_f32_32x32x16_bf16 v[18:33], v[220:223], v[232:235], v[18:33]
	ds_read_b128 v[232:235], v164 offset:59392
	s_waitcnt lgkmcnt(3)
	v_mfma_f32_32x32x16_bf16 v[2:17], v[220:223], v[236:239], v[2:17]
	ds_read_b128 v[236:239], v164 offset:63488
	v_cvt_pk_bf16_f32 v220, v122, v123
	v_cvt_pk_bf16_f32 v221, v124, v125
	v_cvt_pk_bf16_f32 v222, v126, v127
	v_cvt_pk_bf16_f32 v223, v128, v129
	v_cndmask_b32_e64 v164, v190, 1.0, vcc
	v_fmac_f32_e32 v162, v218, v164
	s_waitcnt lgkmcnt(3)
	v_mfma_f32_32x32x16_bf16 v[50:65], v[220:223], v[224:227], v[50:65]
	v_mov_b32_e32 v218, v162
	s_waitcnt lgkmcnt(2)
	v_mfma_f32_32x32x16_bf16 v[34:49], v[220:223], v[228:231], v[34:49]
	s_waitcnt lgkmcnt(1)
	v_mfma_f32_32x32x16_bf16 v[18:33], v[220:223], v[232:235], v[18:33]
	s_waitcnt lgkmcnt(0)
	v_mfma_f32_32x32x16_bf16 v[2:17], v[220:223], v[236:239], v[2:17]
	s_or_b64 exec, exec, s[60:61]
	s_andn2_b64 vcc, exec, s[58:59]
	s_cbranch_vccnz .LBB0_554

; #define K_LOAD(kt) do { sk0 = *(const bf16x8*)(kg + (size_t)(kt) * 8192); sk1 = *(const bf16x8*)(kg + (size_t)(kt) * 8192 + 4096); } while (0)
; #define V_LOAD(kt) do { sv0 = *(const bf16x8*)(vg + (size_t)(kt) * 8192); sv1 = *(const bf16x8*)(vg + (size_t)(kt) * 8192 + 4096); } while (0)
; #define K_STORE(bi) do { char* s_ = kbuf + (bi) * 16384; *(bf16x8*)(s_ + klds) = sk0; *(bf16x8*)(s_ + klds + 4096) = sk1; } while (0)
; #define V_STORE(bi) do { char* s_ = vbuf + (bi) * 16384 - 16384; \
;     s16x4 a0_ = {sv0[0], sv0[1], sv0[2], sv0[3]}, a1_ = {sv0[4], sv0[5], sv0[6], sv0[7]}; \
;     s16x4 b0_ = {sv1[0], sv1[1], sv1[2], sv1[3]}, b1_ = {sv1[4], sv1[5], sv1[6], sv1[7]}; \
;     *(s16x4*)(s_ + vlds0) = a0_; *(s16x4*)(s_ + vlds1) = a1_; *(s16x4*)(s_ + vlds0 + 8192) = b0_; *(s16x4*)(s_ + vlds1 + 8192) = b1_; } while (0)
; DEVI void attn_item(const Params& p, const int l, const int bh, const int qblk, const float lam, const float osc, char* smem) {
;     ...
;   bf16x8 qf[4];
;   {
;     const u16* qp = PBC + (tok0 + (size_t)qblk * 128 + qg * 32 + l31) * 1280 + 512 + h * 128 + m * 64 + hi * 8;
; #pragma unroll
;     for (int d0 = 0; d0 < 4; ++d0) qf[d0] = *(const bf16x8*)(qp + d0 * 16);
;   }
;   const int kkey = tid >> 4, kch = tid & 15;
;   const u16* kg = KT + kkey * 128 + kch * 8;
;   const int klds = (kch >> 3) * 8192 + swz(kkey, kch & 7);
;   const int ve = tid >> 3, vj = tid & 7;
;   const u16* vg = VT + ve * 64 + vj * 8;
;   const int vx = (ve >> 1) & 7;
;   const int vlds0 = 16384 + ve * 128 + ((((vj >> 1) * 2 + 0) ^ vx) << 4) + (vj & 1) * 8;
;   const int vlds1 = 16384 + ve * 128 + ((((vj >> 1) * 2 + 1) ^ vx) << 4) + (vj & 1) * 8;
;   bf16x8 sk0, sk1, sv0, sv1;
;   char* kbuf = stg; char* vbuf = stg + 32768;
;     ...
;   f32x16 o[4];
; #pragma unroll
;   for (int d0 = 0; d0 < 4; ++d0)
; #pragma unroll
;     for (int r = 0; r < 16; ++r) o[d0][r] = 0.f;
;   float m_reg = -1e30f, l_reg = 0.f;
;   const int xq = (l31 >> 1) & 7;
;   f32x16 pA0, pA1, pB0, pB1;
;   K_LOAD(0); V_LOAD(0);
;   {
;     const bf16x8 tk0 = *(const bf16x8*)(kg + (size_t)8192), tk1 = *(const bf16x8*)(kg + (size_t)8192 + 4096);
;     K_STORE(0); V_STORE(0);
;     sk0 = tk0; sk1 = tk1; K_STORE(1);
;   }
;   __syncthreads();
;   QK_TILE(pA0, pA1, 0);
;   __syncthreads();
.LBB0_1313:
	s_or_b64 exec, exec, s[8:9]
	s_waitcnt lgkmcnt(0)
	s_barrier
	ds_read_b32 v2, v169
	s_mov_b64 s[8:9], -1
	s_waitcnt lgkmcnt(0)
	s_barrier
	v_cmp_lt_i32_e32 vcc, s34, v2
	v_readfirstlane_b32 s14, v2
	s_cbranch_vccnz .LBB0_1308
	s_lshl_b32 s9, s14, 1
	s_or_b32 s9, s9, s76
	s_sub_i32 s8, 0x7f, s14
	s_sub_i32 s9, 0x17f, s9
	s_cmpk_lt_i32 s14, 0x80
	s_cselect_b32 s14, s8, s9
	s_cselect_b32 s40, s74, s75
	s_lshl_b32 s77, s14, 1
	s_cmp_gt_u32 s40, 5
	s_cselect_b32 s38, 0x4000, 0
	s_lshl_b64 s[8:9], s[14:15], 7
	s_add_u32 s38, s8, s38
	s_addc_u32 s39, s9, 0
	s_lshl_b32 s8, s40, 7
	s_add_i32 s9, s8, 0xfffffd00
	s_cmp_lt_u32 s40, 6
	s_cselect_b32 s14, s8, s9
	s_lshl_b32 s8, s40, 22
	s_mov_b32 s9, s15
	v_lshl_add_u64 v[20:21], v[170:171], 0, s[8:9]
	v_add_co_u32_e32 v12, vcc, s68, v20
	v_lshl_add_u64 v[10:11], v[172:173], 0, s[8:9]
	s_nop 0
	v_addc_co_u32_e32 v13, vcc, 0, v21, vcc
	v_add_co_u32_e32 v14, vcc, s68, v10
	v_or_b32_e32 v24, s38, v166
	s_nop 0
	v_addc_co_u32_e32 v15, vcc, 0, v11, vcc
	v_mov_b64_e32 v[18:19], s[28:29]
	v_add_co_u32_e32 v22, vcc, s35, v20
	v_mad_u64_u32 v[18:19], s[40:41], v24, s36, v[18:19]
	s_nop 0
	v_addc_co_u32_e32 v23, vcc, 0, v21, vcc
	global_load_dwordx4 v[2:5], v[20:21], off
	global_load_dwordx4 v[6:9], v[10:11], off
	v_add_co_u32_e32 v20, vcc, s69, v20
	v_mad_u32_u24 v19, s39, v208, v19
	global_load_dwordx4 v[10:13], v[12:13], off
	s_nop 0
	global_load_dwordx4 v[14:17], v[14:15], off
	v_addc_co_u32_e32 v21, vcc, 0, v21, vcc
	global_load_dwordx4 v[146:149], v[22:23], off
	global_load_dwordx4 v[150:153], v[20:21], off
	v_lshl_add_u64 v[18:19], s[14:15], 1, v[18:19]
	v_mov_b32_e32 v181, v169
	v_lshl_add_u64 v[18:19], v[18:19], 0, v[180:181]
	v_mov_b32_e32 v183, v169
	v_lshl_add_u64 v[18:19], v[18:19], 0, v[182:183]
	v_add_co_u32_e32 v20, vcc, s37, v18
	v_add_u32_e32 v181, v198, v199
	s_nop 0
	v_addc_co_u32_e32 v21, vcc, 0, v19, vcc
	global_load_dwordx4 v[130:133], v[20:21], off offset:1024
	v_lshl_add_u64 v[18:19], v[18:19], 0, s[16:17]
	global_load_dwordx4 v[134:137], v[18:19], off offset:32
	global_load_dwordx4 v[138:141], v[18:19], off offset:64
	global_load_dwordx4 v[142:145], v[18:19], off offset:96
	v_add_u32_e32 v183, v198, v200
	v_add_u32_e32 v212, v198, v201
	v_add_u32_e32 v213, v198, v202
	s_mov_b32 s52, 0
	s_mov_b32 s53, s52
	s_mov_b32 s54, s52
	s_mov_b32 s55, s52
	s_mov_b32 s56, s52
	s_mov_b32 s57, s52
	s_mov_b32 s58, s52
	s_mov_b32 s59, s52
	s_mov_b32 s60, s52
	s_mov_b32 s61, s52
	s_mov_b32 s62, s52
	s_mov_b32 s63, s52
	s_mov_b32 s64, s52
	s_mov_b32 s65, s52
	s_mov_b32 s66, s52
	s_mov_b32 s67, s52
	v_mov_b64_e32 v[50:51], s[52:53]
	v_mov_b64_e32 v[52:53], s[54:55]
	v_mov_b64_e32 v[54:55], s[56:57]
	v_mov_b64_e32 v[56:57], s[58:59]
	v_mov_b64_e32 v[58:59], s[60:61]
	v_mov_b64_e32 v[60:61], s[62:63]
	v_mov_b64_e32 v[62:63], s[64:65]
	v_mov_b64_e32 v[64:65], s[66:67]
	s_add_i32 s53, s77, 2
	s_add_u32 s40, s28, s8
	v_mov_b64_e32 v[34:35], v[50:51]
	v_mov_b64_e32 v[18:19], v[50:51]
	v_add_u32_e32 v214, s77, v194
	s_addc_u32 s41, s29, 0
	s_add_u32 s40, s40, 0x22a08000
	s_addc_u32 s41, s41, 0
	v_mov_b32_e32 v215, 0
	v_mov_b32_e32 v188, 0xf149f2ca
	v_mov_b64_e32 v[36:37], v[52:53]
	v_mov_b64_e32 v[38:39], v[54:55]
	v_mov_b64_e32 v[40:41], v[56:57]
	v_mov_b64_e32 v[42:43], v[58:59]
	v_mov_b64_e32 v[44:45], v[60:61]
	v_mov_b64_e32 v[46:47], v[62:63]
	v_mov_b64_e32 v[48:49], v[64:65]
	v_mov_b64_e32 v[20:21], v[52:53]
	s_waitcnt vmcnt(9)
	ds_write_b128 v209, v[2:5] offset:2048
	s_waitcnt vmcnt(8)
	ds_write_b128 v253, v[6:9] offset:34816
	s_waitcnt vmcnt(7)
	ds_write_b128 v209, v[10:13] offset:6144
	s_waitcnt vmcnt(6)
	ds_write_b128 v253, v[14:17] offset:43008
	s_waitcnt vmcnt(5)
	ds_write_b128 v209, v[146:149] offset:18432
	s_waitcnt vmcnt(4)
	ds_write_b128 v209, v[150:153] offset:22528
	s_waitcnt lgkmcnt(0)
	s_barrier
	ds_read_b128 v[2:5], v181 offset:2048
	ds_read_b128 v[6:9], v181 offset:6144
	s_waitcnt vmcnt(3) lgkmcnt(1)
	v_mfma_f32_32x32x16_bf16 v[66:81], v[2:5], v[130:133], 0
	v_mov_b64_e32 v[22:23], v[54:55]
	v_mov_b64_e32 v[24:25], v[56:57]
	v_mov_b64_e32 v[26:27], v[58:59]
	v_mov_b64_e32 v[28:29], v[60:61]
	v_mov_b64_e32 v[30:31], v[62:63]
	v_mov_b64_e32 v[32:33], v[64:65]
	s_waitcnt lgkmcnt(0)
	v_mfma_f32_32x32x16_bf16 v[98:113], v[6:9], v[130:133], 0
	ds_read_b128 v[2:5], v183 offset:2048
	ds_read_b128 v[6:9], v183 offset:6144
	s_waitcnt vmcnt(2) lgkmcnt(1)
	v_mfma_f32_32x32x16_bf16 v[66:81], v[2:5], v[134:137], v[66:81]
	ds_read_b128 v[2:5], v212 offset:2048
	s_waitcnt lgkmcnt(1)
	v_mfma_f32_32x32x16_bf16 v[98:113], v[6:9], v[134:137], v[98:113]
	ds_read_b128 v[6:9], v212 offset:6144
	s_waitcnt vmcnt(1) lgkmcnt(1)
	v_mfma_f32_32x32x16_bf16 v[66:81], v[2:5], v[138:141], v[66:81]
	ds_read_b128 v[2:5], v213 offset:2048
	s_waitcnt lgkmcnt(1)
	v_mfma_f32_32x32x16_bf16 v[98:113], v[6:9], v[138:141], v[98:113]
	ds_read_b128 v[6:9], v213 offset:6144
	s_waitcnt lgkmcnt(0)
	s_barrier
	s_waitcnt vmcnt(0)
	v_mfma_f32_32x32x16_bf16 v[66:81], v[2:5], v[142:145], v[66:81]
	v_mfma_f32_32x32x16_bf16 v[98:113], v[6:9], v[142:145], v[98:113]
	v_mov_b64_e32 v[2:3], v[50:51]
	v_mov_b64_e32 v[4:5], v[52:53]
	v_mov_b64_e32 v[6:7], v[54:55]
	v_mov_b64_e32 v[8:9], v[56:57]
	v_mov_b64_e32 v[10:11], v[58:59]
	v_mov_b64_e32 v[12:13], v[60:61]
	v_mov_b64_e32 v[14:15], v[62:63]
	v_mov_b64_e32 v[16:17], v[64:65]
	s_nop 15
	s_nop 15
	v_max_f32_e32 v247, v67, v67
	v_max_f32_e32 v248, v66, v66
	v_max_f32_e32 v247, v248, v247
	v_max3_f32 v247, v247, v68, v69
	v_max3_f32 v247, v247, v70, v71
	v_max3_f32 v247, v247, v72, v73
	v_max3_f32 v247, v247, v74, v75
	v_max3_f32 v247, v247, v76, v77
	v_max3_f32 v247, v247, v78, v79
	v_max3_f32 v249, v247, v80, v81
	v_max3_f32 v247, v249, v98, v99
	v_max3_f32 v247, v247, v100, v101
	v_max3_f32 v247, v247, v102, v103
	v_max3_f32 v247, v247, v104, v105
	v_max3_f32 v247, v247, v106, v107
	v_max3_f32 v247, v247, v108, v109
	v_max3_f32 v247, v247, v110, v111
	v_max3_f32 v249, v247, v112, v113
	s_branch .LBB0_1316

.LBB0_1318:
	s_add_u32 m0, s101, 0xc810
	s_nop 0
	global_load_lds_dwordx4 v243, s[40:41]
	s_add_u32 m0, s101, 0xe810
	s_nop 0
	global_load_lds_dwordx4 v244, s[40:41]
	v_cmp_le_u32_e32 vcc, s52, v214
	s_and_saveexec_b64 s[8:9], vcc
	s_cbranch_execz .LBB0_1324
	s_waitcnt lgkmcnt(1)
	v_mfma_f32_32x32x16_bf16 v[82:97], v[82:85], v[130:133], 0
	ds_read_b128 v[118:121], v183 offset:18432
	ds_read_b128 v[218:221], v183 offset:22528
	s_waitcnt lgkmcnt(1)
	v_mfma_f32_32x32x16_bf16 v[82:97], v[118:121], v[134:137], v[82:97]
	v_mov_b32_e32 v122, v249
	v_mov_b32_e32 v118, v249
	s_nop 1
	v_permlane32_swap_b32_e32 v122, v118
	ds_read_b128 v[222:225], v212 offset:22528
	ds_read_b128 v[226:229], v213 offset:22528
	v_max_f32_e32 v123, v118, v118
	ds_read_b128 v[118:121], v212 offset:18432
	s_waitcnt lgkmcnt(0)
	v_mfma_f32_32x32x16_bf16 v[82:97], v[118:121], v[138:141], v[82:97]
	v_max_f32_e32 v118, v122, v122
	v_max_f32_e32 v118, v118, v123
	v_sub_f32_e32 v120, v118, v188
	v_cmp_ge_f32_e32 vcc, s70, v120
	v_max_f32_e32 v119, v188, v188
	s_cmp_eq_u64 vcc, exec
	v_max_f32_e32 v118, v119, v118
	s_cselect_b64 vcc, -1, 0
	v_cndmask_b32_e32 v216, v118, v188, vcc
	v_sub_f32_e32 v118, v188, v216
	v_mul_f32_e32 v188, 0xbe38aa3b, v216
	v_mul_f32_e32 v189, 0x3e38aa3b, v118
	ds_read_b128 v[118:121], v213 offset:18432
	s_waitcnt lgkmcnt(0)
	v_mfma_f32_32x32x16_bf16 v[82:97], v[118:121], v[142:145], v[82:97]
	v_fma_f32 v66, v66, s18, v188
	v_fma_f32 v67, v67, s18, v188
	v_fma_f32 v68, v68, s18, v188
	v_fma_f32 v69, v69, s18, v188
	v_exp_f32_e32 v66, v66
	v_exp_f32_e32 v67, v67
	v_pk_fma_f32 v[70:71], v[70:71], s[18:19], v[188:189] op_sel_hi:[1,0,0]
	v_exp_f32_e32 v68, v68
	v_exp_f32_e32 v69, v69
	v_pk_fma_f32 v[72:73], v[72:73], s[18:19], v[188:189] op_sel_hi:[1,0,0]
	v_exp_f32_e32 v70, v70
	v_exp_f32_e32 v71, v71
	v_pk_fma_f32 v[74:75], v[74:75], s[18:19], v[188:189] op_sel_hi:[1,0,0]
	v_exp_f32_e32 v72, v72
	v_exp_f32_e32 v73, v73
	v_exp_f32_e32 v74, v74
	v_exp_f32_e32 v75, v75
	v_pk_add_f32 v[118:119], v[66:67], 0 op_sel_hi:[1,0]
	v_exp_f32_e32 v217, v189
	v_pk_add_f32 v[118:119], v[68:69], v[118:119]
	s_nop 0
	v_pk_add_f32 v[118:119], v[70:71], v[118:119]
	s_nop 0
	v_pk_add_f32 v[118:119], v[72:73], v[118:119]
	s_nop 0
	v_pk_add_f32 v[230:231], v[74:75], v[118:119]
	v_mfma_f32_32x32x16_bf16 v[114:129], v[114:117], v[130:133], 0
	v_mfma_f32_32x32x16_bf16 v[114:129], v[218:221], v[134:137], v[114:129]
	v_mfma_f32_32x32x16_bf16 v[114:129], v[222:225], v[138:141], v[114:129]
	v_mfma_f32_32x32x16_bf16 v[114:129], v[226:229], v[142:145], v[114:129]
	v_fma_f32 v76, v76, s18, v188
	v_fma_f32 v77, v77, s18, v188
	v_fma_f32 v78, v78, s18, v188
	v_fma_f32 v79, v79, s18, v188
	v_exp_f32_e32 v76, v76
	v_exp_f32_e32 v77, v77
	v_pk_fma_f32 v[80:81], v[80:81], s[18:19], v[188:189] op_sel_hi:[1,0,0]
	v_exp_f32_e32 v78, v78
	v_exp_f32_e32 v79, v79
	v_exp_f32_e32 v80, v80
	v_exp_f32_e32 v81, v81
	v_pk_fma_f32 v[98:99], v[98:99], s[18:19], v[188:189] op_sel_hi:[1,0,0]
	v_pk_fma_f32 v[100:101], v[100:101], s[18:19], v[188:189] op_sel_hi:[1,0,0]
	v_exp_f32_e32 v98, v98
	v_exp_f32_e32 v99, v99
	v_pk_add_f32 v[230:231], v[76:77], v[230:231]
	v_exp_f32_e32 v100, v100
	v_exp_f32_e32 v101, v101
	v_pk_add_f32 v[230:231], v[78:79], v[230:231]
	s_nop 0
	v_pk_add_f32 v[230:231], v[80:81], v[230:231]
	s_nop 0
	v_pk_add_f32 v[230:231], v[98:99], v[230:231]
	s_nop 0
	v_pk_add_f32 v[230:231], v[100:101], v[230:231]
	v_pk_fma_f32 v[102:103], v[102:103], s[18:19], v[188:189] op_sel_hi:[1,0,0]
	v_pk_fma_f32 v[104:105], v[104:105], s[18:19], v[188:189] op_sel_hi:[1,0,0]
	v_exp_f32_e32 v102, v102
	v_exp_f32_e32 v103, v103
	v_exp_f32_e32 v104, v104
	v_exp_f32_e32 v105, v105
	v_pk_fma_f32 v[106:107], v[106:107], s[18:19], v[188:189] op_sel_hi:[1,0,0]
	v_pk_fma_f32 v[108:109], v[108:109], s[18:19], v[188:189] op_sel_hi:[1,0,0]
	v_exp_f32_e32 v106, v106
	v_exp_f32_e32 v107, v107
	v_exp_f32_e32 v108, v108
	v_exp_f32_e32 v109, v109
	v_pk_fma_f32 v[110:111], v[110:111], s[18:19], v[188:189] op_sel_hi:[1,0,0]
	v_pk_add_f32 v[218:219], v[102:103], v[230:231]
	v_exp_f32_e32 v110, v110
	v_exp_f32_e32 v111, v111
	v_pk_add_f32 v[218:219], v[104:105], v[218:219]
	s_nop 0
	v_pk_add_f32 v[218:219], v[106:107], v[218:219]
	s_nop 0
	v_pk_add_f32 v[218:219], v[108:109], v[218:219]
	s_nop 0
	v_pk_add_f32 v[218:219], v[110:111], v[218:219]
	v_pk_fma_f32 v[112:113], v[112:113], s[18:19], v[188:189] op_sel_hi:[1,0,0]
	s_nop 0
	v_exp_f32_e32 v112, v112
	v_exp_f32_e32 v113, v113
	s_nop 0
	v_pk_add_f32 v[188:189], v[112:113], v[218:219]
	s_nop 0
	v_pk_add_f32 v[188:189], v[188:189], v[188:189] op_sel:[0,1] op_sel_hi:[1,0]
	s_nop 0
	v_mov_b32_e32 v189, v188
	s_nop 1
	v_permlane32_swap_b32_e32 v188, v189
	s_cbranch_vccnz .LBB0_1323
	s_waitcnt lgkmcnt(0)
	s_and_saveexec_b64 s[56:57], s[2:3]
	ds_write_b32 v204, v217
	s_or_b64 exec, exec, s[56:57]
	s_waitcnt lgkmcnt(0)
	v_add_u32_e32 v230, v203, v191
	ds_read_b128 v[218:221], v230 offset:96
	ds_read_b128 v[222:225], v230 offset:64
	ds_read_b128 v[226:229], v230 offset:32
	ds_read_b128 v[230:233], v230
	s_waitcnt lgkmcnt(0)
	s_waitcnt lgkmcnt(3)
	v_pk_mul_f32 v[62:63], v[62:63], v[218:219]
	s_waitcnt lgkmcnt(2)
	v_pk_mul_f32 v[58:59], v[58:59], v[222:223]
	s_waitcnt lgkmcnt(1)
	v_pk_mul_f32 v[54:55], v[54:55], v[226:227]
	v_pk_mul_f32 v[64:65], v[64:65], v[220:221]
	v_pk_mul_f32 v[60:61], v[60:61], v[224:225]
	v_pk_mul_f32 v[56:57], v[56:57], v[228:229]
	s_waitcnt lgkmcnt(0)
	v_pk_mul_f32 v[52:53], v[52:53], v[232:233]
	v_pk_mul_f32 v[50:51], v[50:51], v[230:231]
	v_pk_mul_f32 v[46:47], v[46:47], v[218:219]
	v_pk_mul_f32 v[42:43], v[42:43], v[222:223]
	v_pk_mul_f32 v[38:39], v[38:39], v[226:227]
	v_pk_mul_f32 v[48:49], v[48:49], v[220:221]
	v_pk_mul_f32 v[44:45], v[44:45], v[224:225]
	v_pk_mul_f32 v[40:41], v[40:41], v[228:229]
	v_pk_mul_f32 v[36:37], v[36:37], v[232:233]
	v_pk_mul_f32 v[34:35], v[34:35], v[230:231]
	v_pk_mul_f32 v[30:31], v[30:31], v[218:219]
	v_pk_mul_f32 v[26:27], v[26:27], v[222:223]
	v_pk_mul_f32 v[22:23], v[22:23], v[226:227]
	v_pk_mul_f32 v[32:33], v[32:33], v[220:221]
	v_pk_mul_f32 v[28:29], v[28:29], v[224:225]
	v_pk_mul_f32 v[24:25], v[24:25], v[228:229]
	v_pk_mul_f32 v[20:21], v[20:21], v[232:233]
	v_pk_mul_f32 v[18:19], v[18:19], v[230:231]
	v_pk_mul_f32 v[14:15], v[14:15], v[218:219]
	v_pk_mul_f32 v[10:11], v[10:11], v[222:223]
	v_pk_mul_f32 v[6:7], v[6:7], v[226:227]
	v_pk_mul_f32 v[16:17], v[16:17], v[220:221]
	v_pk_mul_f32 v[12:13], v[12:13], v[224:225]
	v_pk_mul_f32 v[8:9], v[8:9], v[228:229]
	v_pk_mul_f32 v[4:5], v[4:5], v[232:233]
	v_pk_mul_f32 v[2:3], v[2:3], v[230:231]
.LBB0_1323:
	v_add_u32_e32 v234, v197, v199
	ds_read_b128 v[222:225], v234 offset:34816
	ds_read_b128 v[226:229], v234 offset:38912
	ds_read_b128 v[230:233], v234 offset:43008
	ds_read_b128 v[234:237], v234 offset:47104
	v_add_u32_e32 v238, v197, v200
	v_cvt_pk_bf16_f32 v218, v66, v67
	v_cvt_pk_bf16_f32 v219, v68, v69
	v_cvt_pk_bf16_f32 v220, v70, v71
	v_cvt_pk_bf16_f32 v221, v72, v73
	v_cndmask_b32_e64 v217, v217, 1.0, vcc
	s_waitcnt lgkmcnt(3)
	v_mfma_f32_32x32x16_bf16 v[50:65], v[218:221], v[222:225], v[50:65]
	ds_read_b128 v[222:225], v238 offset:34816
	v_max_f32_e32 v247, v83, v83
	v_max_f32_e32 v248, v82, v82
	v_add_f32_e32 v189, v188, v189
	v_fmac_f32_e32 v189, v215, v217
	v_mov_b32_e32 v188, v216
	v_mov_b32_e32 v215, v189
	s_waitcnt lgkmcnt(3)
	v_mfma_f32_32x32x16_bf16 v[34:49], v[218:221], v[226:229], v[34:49]
	ds_read_b128 v[226:229], v238 offset:38912
	v_max_f32_e32 v247, v248, v247
	v_max3_f32 v247, v247, v84, v85
	s_waitcnt lgkmcnt(3)
	v_mfma_f32_32x32x16_bf16 v[18:33], v[218:221], v[230:233], v[18:33]
	ds_read_b128 v[230:233], v238 offset:43008
	v_max3_f32 v247, v247, v86, v87
	v_max3_f32 v247, v247, v88, v89
	s_waitcnt lgkmcnt(3)
	v_mfma_f32_32x32x16_bf16 v[2:17], v[218:221], v[234:237], v[2:17]
	ds_read_b128 v[234:237], v238 offset:47104
	v_max3_f32 v247, v247, v90, v91
	v_max3_f32 v247, v247, v92, v93
	v_add_u32_e32 v238, v197, v201
	v_cvt_pk_bf16_f32 v218, v74, v75
	v_cvt_pk_bf16_f32 v219, v76, v77
	v_cvt_pk_bf16_f32 v220, v78, v79
	v_cvt_pk_bf16_f32 v221, v80, v81
	s_waitcnt lgkmcnt(3)
	v_mfma_f32_32x32x16_bf16 v[50:65], v[218:221], v[222:225], v[50:65]
	ds_read_b128 v[222:225], v238 offset:34816
	v_max3_f32 v247, v247, v94, v95
	v_max3_f32 v250, v247, v96, v97
	s_waitcnt lgkmcnt(3)
	v_mfma_f32_32x32x16_bf16 v[34:49], v[218:221], v[226:229], v[34:49]
	ds_read_b128 v[226:229], v238 offset:38912
	v_max3_f32 v247, v250, v114, v115
	v_max3_f32 v247, v247, v116, v117
	s_waitcnt lgkmcnt(3)
	v_mfma_f32_32x32x16_bf16 v[18:33], v[218:221], v[230:233], v[18:33]
	ds_read_b128 v[230:233], v238 offset:43008
	v_max3_f32 v247, v247, v118, v119
	v_max3_f32 v247, v247, v120, v121
	s_waitcnt lgkmcnt(3)
	v_mfma_f32_32x32x16_bf16 v[2:17], v[218:221], v[234:237], v[2:17]
	ds_read_b128 v[234:237], v238 offset:47104
	v_max3_f32 v247, v247, v122, v123
	v_max3_f32 v247, v247, v124, v125
	v_add_u32_e32 v238, v197, v202
	v_cvt_pk_bf16_f32 v218, v98, v99
	v_cvt_pk_bf16_f32 v219, v100, v101
	v_cvt_pk_bf16_f32 v220, v102, v103
	v_cvt_pk_bf16_f32 v221, v104, v105
	s_waitcnt lgkmcnt(3)
	v_mfma_f32_32x32x16_bf16 v[50:65], v[218:221], v[222:225], v[50:65]
	ds_read_b128 v[222:225], v238 offset:34816
	v_max3_f32 v247, v247, v126, v127
	v_max3_f32 v250, v247, v128, v129
	s_waitcnt lgkmcnt(3)
	v_mfma_f32_32x32x16_bf16 v[34:49], v[218:221], v[226:229], v[34:49]
	ds_read_b128 v[226:229], v238 offset:38912
	s_waitcnt lgkmcnt(3)
	v_mfma_f32_32x32x16_bf16 v[18:33], v[218:221], v[230:233], v[18:33]
	ds_read_b128 v[230:233], v238 offset:43008
	s_waitcnt lgkmcnt(3)
	v_mfma_f32_32x32x16_bf16 v[2:17], v[218:221], v[234:237], v[2:17]
	ds_read_b128 v[234:237], v238 offset:47104
	v_cvt_pk_bf16_f32 v218, v106, v107
	v_cvt_pk_bf16_f32 v219, v108, v109
	v_cvt_pk_bf16_f32 v220, v110, v111
	v_cvt_pk_bf16_f32 v221, v112, v113
	s_waitcnt lgkmcnt(3)
	v_mfma_f32_32x32x16_bf16 v[50:65], v[218:221], v[222:225], v[50:65]
	s_waitcnt lgkmcnt(2)
	v_mfma_f32_32x32x16_bf16 v[34:49], v[218:221], v[226:229], v[34:49]
	s_waitcnt lgkmcnt(1)
	v_mfma_f32_32x32x16_bf16 v[18:33], v[218:221], v[230:233], v[18:33]
	s_waitcnt lgkmcnt(0)
	v_mfma_f32_32x32x16_bf16 v[2:17], v[218:221], v[234:237], v[2:17]

.LBB0_1333:
	s_waitcnt lgkmcnt(1)
	v_mfma_f32_32x32x16_bf16 v[66:81], v[66:69], v[130:133], 0
	ds_read_b128 v[102:105], v183 offset:2048
	ds_read_b128 v[216:219], v183 offset:6144
	s_waitcnt lgkmcnt(1)
	v_mfma_f32_32x32x16_bf16 v[66:81], v[102:105], v[134:137], v[66:81]
	v_mov_b32_e32 v106, v250
	v_mov_b32_e32 v102, v250
	s_nop 1
	v_permlane32_swap_b32_e32 v106, v102
	ds_read_b128 v[220:223], v212 offset:6144
	ds_read_b128 v[224:227], v213 offset:6144
	v_max_f32_e32 v107, v102, v102
	ds_read_b128 v[102:105], v212 offset:2048
	s_waitcnt lgkmcnt(0)
	v_mfma_f32_32x32x16_bf16 v[66:81], v[102:105], v[138:141], v[66:81]
	v_max_f32_e32 v102, v106, v106
	v_max_f32_e32 v102, v102, v107
	v_sub_f32_e32 v104, v102, v188
	v_cmp_ge_f32_e32 vcc, s70, v104
	v_max_f32_e32 v103, v188, v188
	s_cmp_eq_u64 vcc, exec
	v_max_f32_e32 v102, v103, v102
	s_cselect_b64 vcc, -1, 0
	v_cndmask_b32_e32 v186, v102, v188, vcc
	v_sub_f32_e32 v102, v188, v186
	v_mul_f32_e32 v184, 0xbe38aa3b, v186
	v_mul_f32_e32 v185, 0x3e38aa3b, v102
	ds_read_b128 v[102:105], v213 offset:2048
	s_waitcnt lgkmcnt(0)
	v_mfma_f32_32x32x16_bf16 v[66:81], v[102:105], v[142:145], v[66:81]
	v_fma_f32 v82, v82, s18, v184
	v_fma_f32 v83, v83, s18, v184
	v_fma_f32 v84, v84, s18, v184
	v_fma_f32 v85, v85, s18, v184
	v_exp_f32_e32 v82, v82
	v_exp_f32_e32 v83, v83
	v_pk_fma_f32 v[86:87], v[86:87], s[18:19], v[184:185] op_sel_hi:[1,0,0]
	v_exp_f32_e32 v84, v84
	v_exp_f32_e32 v85, v85
	v_pk_fma_f32 v[88:89], v[88:89], s[18:19], v[184:185] op_sel_hi:[1,0,0]
	v_exp_f32_e32 v86, v86
	v_exp_f32_e32 v87, v87
	v_pk_fma_f32 v[90:91], v[90:91], s[18:19], v[184:185] op_sel_hi:[1,0,0]
	v_exp_f32_e32 v88, v88
	v_exp_f32_e32 v89, v89
	v_exp_f32_e32 v90, v90
	v_exp_f32_e32 v91, v91
	v_pk_add_f32 v[102:103], v[82:83], 0 op_sel_hi:[1,0]
	v_exp_f32_e32 v187, v185
	v_pk_add_f32 v[102:103], v[84:85], v[102:103]
	s_nop 0
	v_pk_add_f32 v[102:103], v[86:87], v[102:103]
	s_nop 0
	v_pk_add_f32 v[102:103], v[88:89], v[102:103]
	s_nop 0
	v_pk_add_f32 v[188:189], v[90:91], v[102:103]
	v_mfma_f32_32x32x16_bf16 v[98:113], v[98:101], v[130:133], 0
	v_mfma_f32_32x32x16_bf16 v[98:113], v[216:219], v[134:137], v[98:113]
	v_mfma_f32_32x32x16_bf16 v[98:113], v[220:223], v[138:141], v[98:113]
	v_mfma_f32_32x32x16_bf16 v[98:113], v[224:227], v[142:145], v[98:113]
	v_fma_f32 v92, v92, s18, v184
	v_fma_f32 v93, v93, s18, v184
	v_fma_f32 v94, v94, s18, v184
	v_fma_f32 v95, v95, s18, v184
	v_exp_f32_e32 v92, v92
	v_exp_f32_e32 v93, v93
	v_pk_fma_f32 v[96:97], v[96:97], s[18:19], v[184:185] op_sel_hi:[1,0,0]
	v_exp_f32_e32 v94, v94
	v_exp_f32_e32 v95, v95
	v_exp_f32_e32 v96, v96
	v_exp_f32_e32 v97, v97
	v_pk_fma_f32 v[114:115], v[114:115], s[18:19], v[184:185] op_sel_hi:[1,0,0]
	v_pk_fma_f32 v[116:117], v[116:117], s[18:19], v[184:185] op_sel_hi:[1,0,0]
	v_exp_f32_e32 v114, v114
	v_exp_f32_e32 v115, v115
	v_pk_add_f32 v[188:189], v[92:93], v[188:189]
	v_exp_f32_e32 v116, v116
	v_exp_f32_e32 v117, v117
	v_pk_add_f32 v[188:189], v[94:95], v[188:189]
	s_nop 0
	v_pk_add_f32 v[188:189], v[96:97], v[188:189]
	s_nop 0
	v_pk_add_f32 v[188:189], v[114:115], v[188:189]
	s_nop 0
	v_pk_add_f32 v[188:189], v[116:117], v[188:189]
	v_pk_fma_f32 v[118:119], v[118:119], s[18:19], v[184:185] op_sel_hi:[1,0,0]
	v_pk_fma_f32 v[120:121], v[120:121], s[18:19], v[184:185] op_sel_hi:[1,0,0]
	v_exp_f32_e32 v118, v118
	v_exp_f32_e32 v119, v119
	v_exp_f32_e32 v120, v120
	v_exp_f32_e32 v121, v121
	v_pk_fma_f32 v[122:123], v[122:123], s[18:19], v[184:185] op_sel_hi:[1,0,0]
	v_pk_fma_f32 v[124:125], v[124:125], s[18:19], v[184:185] op_sel_hi:[1,0,0]
	v_exp_f32_e32 v122, v122
	v_exp_f32_e32 v123, v123
	v_exp_f32_e32 v124, v124
	v_exp_f32_e32 v125, v125
	v_pk_fma_f32 v[126:127], v[126:127], s[18:19], v[184:185] op_sel_hi:[1,0,0]
	v_pk_add_f32 v[188:189], v[118:119], v[188:189]
	v_exp_f32_e32 v126, v126
	v_exp_f32_e32 v127, v127
	v_pk_add_f32 v[188:189], v[120:121], v[188:189]
	s_nop 0
	v_pk_add_f32 v[188:189], v[122:123], v[188:189]
	s_nop 0
	v_pk_add_f32 v[188:189], v[124:125], v[188:189]
	s_nop 0
	v_pk_add_f32 v[188:189], v[126:127], v[188:189]
	v_pk_fma_f32 v[128:129], v[128:129], s[18:19], v[184:185] op_sel_hi:[1,0,0]
	s_nop 0
	v_exp_f32_e32 v128, v128
	v_exp_f32_e32 v129, v129
	s_nop 0
	v_pk_add_f32 v[184:185], v[128:129], v[188:189]
	s_nop 0
	v_pk_add_f32 v[184:185], v[184:185], v[184:185] op_sel:[0,1] op_sel_hi:[1,0]
	s_nop 0
	v_mov_b32_e32 v185, v184
	s_nop 1
	v_permlane32_swap_b32_e32 v184, v185
	s_cbranch_vccnz .LBB0_1337
	s_waitcnt lgkmcnt(0)
	s_and_saveexec_b64 s[58:59], s[2:3]
	ds_write_b32 v204, v187
	s_or_b64 exec, exec, s[58:59]
	s_waitcnt lgkmcnt(0)
	v_add_u32_e32 v188, v203, v191
	ds_read_b128 v[216:219], v188 offset:96
	ds_read_b128 v[220:223], v188 offset:64
	ds_read_b128 v[224:227], v188 offset:32
	ds_read_b128 v[228:231], v188
	s_waitcnt lgkmcnt(0)
	s_waitcnt lgkmcnt(3)
	v_pk_mul_f32 v[62:63], v[62:63], v[216:217]
	s_waitcnt lgkmcnt(2)
	v_pk_mul_f32 v[58:59], v[58:59], v[220:221]
	s_waitcnt lgkmcnt(1)
	v_pk_mul_f32 v[54:55], v[54:55], v[224:225]
	v_pk_mul_f32 v[64:65], v[64:65], v[218:219]
	v_pk_mul_f32 v[60:61], v[60:61], v[222:223]
	v_pk_mul_f32 v[56:57], v[56:57], v[226:227]
	s_waitcnt lgkmcnt(0)
	v_pk_mul_f32 v[52:53], v[52:53], v[230:231]
	v_pk_mul_f32 v[50:51], v[50:51], v[228:229]
	v_pk_mul_f32 v[46:47], v[46:47], v[216:217]
	v_pk_mul_f32 v[42:43], v[42:43], v[220:221]
	v_pk_mul_f32 v[38:39], v[38:39], v[224:225]
	v_pk_mul_f32 v[48:49], v[48:49], v[218:219]
	v_pk_mul_f32 v[44:45], v[44:45], v[222:223]
	v_pk_mul_f32 v[40:41], v[40:41], v[226:227]
	v_pk_mul_f32 v[36:37], v[36:37], v[230:231]
	v_pk_mul_f32 v[34:35], v[34:35], v[228:229]
	v_pk_mul_f32 v[30:31], v[30:31], v[216:217]
	v_pk_mul_f32 v[26:27], v[26:27], v[220:221]
	v_pk_mul_f32 v[22:23], v[22:23], v[224:225]
	v_pk_mul_f32 v[32:33], v[32:33], v[218:219]
	v_pk_mul_f32 v[28:29], v[28:29], v[222:223]
	v_pk_mul_f32 v[24:25], v[24:25], v[226:227]
	v_pk_mul_f32 v[20:21], v[20:21], v[230:231]
	v_pk_mul_f32 v[18:19], v[18:19], v[228:229]
	v_pk_mul_f32 v[14:15], v[14:15], v[216:217]
	v_pk_mul_f32 v[10:11], v[10:11], v[220:221]
	v_pk_mul_f32 v[6:7], v[6:7], v[224:225]
	v_pk_mul_f32 v[16:17], v[16:17], v[218:219]
	v_pk_mul_f32 v[12:13], v[12:13], v[222:223]
	v_pk_mul_f32 v[8:9], v[8:9], v[226:227]
	v_pk_mul_f32 v[4:5], v[4:5], v[230:231]
	v_pk_mul_f32 v[2:3], v[2:3], v[228:229]
.LBB0_1337:
	v_add_u32_e32 v188, v197, v199
	ds_read_b128 v[220:223], v188 offset:51200
	ds_read_b128 v[224:227], v188 offset:55296
	ds_read_b128 v[228:231], v188 offset:59392
	ds_read_b128 v[232:235], v188 offset:63488
	v_add_u32_e32 v188, v197, v200
	v_cvt_pk_bf16_f32 v216, v82, v83
	v_cvt_pk_bf16_f32 v217, v84, v85
	v_cvt_pk_bf16_f32 v218, v86, v87
	v_cvt_pk_bf16_f32 v219, v88, v89
	v_cndmask_b32_e64 v187, v187, 1.0, vcc
	s_waitcnt lgkmcnt(3)
	v_mfma_f32_32x32x16_bf16 v[50:65], v[216:219], v[220:223], v[50:65]
	ds_read_b128 v[220:223], v188 offset:51200
	v_max_f32_e32 v247, v67, v67
	v_max_f32_e32 v248, v66, v66
	v_add_f32_e32 v184, v184, v185
	v_fmac_f32_e32 v184, v215, v187
	v_mov_b32_e32 v215, v184
	s_waitcnt lgkmcnt(3)
	v_mfma_f32_32x32x16_bf16 v[34:49], v[216:219], v[224:227], v[34:49]
	ds_read_b128 v[224:227], v188 offset:55296
	v_max_f32_e32 v247, v248, v247
	v_max3_f32 v247, v247, v68, v69
	s_waitcnt lgkmcnt(3)
	v_mfma_f32_32x32x16_bf16 v[18:33], v[216:219], v[228:231], v[18:33]
	ds_read_b128 v[228:231], v188 offset:59392
	v_max3_f32 v247, v247, v70, v71
	v_max3_f32 v247, v247, v72, v73
	s_waitcnt lgkmcnt(3)
	v_mfma_f32_32x32x16_bf16 v[2:17], v[216:219], v[232:235], v[2:17]
	ds_read_b128 v[232:235], v188 offset:63488
	v_max3_f32 v247, v247, v74, v75
	v_max3_f32 v247, v247, v76, v77
	v_add_u32_e32 v188, v197, v201
	v_cvt_pk_bf16_f32 v216, v90, v91
	v_cvt_pk_bf16_f32 v217, v92, v93
	v_cvt_pk_bf16_f32 v218, v94, v95
	v_cvt_pk_bf16_f32 v219, v96, v97
	s_waitcnt lgkmcnt(3)
	v_mfma_f32_32x32x16_bf16 v[50:65], v[216:219], v[220:223], v[50:65]
	ds_read_b128 v[220:223], v188 offset:51200
	v_max3_f32 v247, v247, v78, v79
	v_max3_f32 v249, v247, v80, v81
	s_waitcnt lgkmcnt(3)
	v_mfma_f32_32x32x16_bf16 v[34:49], v[216:219], v[224:227], v[34:49]
	ds_read_b128 v[224:227], v188 offset:55296
	v_max3_f32 v247, v249, v98, v99
	v_max3_f32 v247, v247, v100, v101
	s_waitcnt lgkmcnt(3)
	v_mfma_f32_32x32x16_bf16 v[18:33], v[216:219], v[228:231], v[18:33]
	ds_read_b128 v[228:231], v188 offset:59392
	v_max3_f32 v247, v247, v102, v103
	v_max3_f32 v247, v247, v104, v105
	s_waitcnt lgkmcnt(3)
	v_mfma_f32_32x32x16_bf16 v[2:17], v[216:219], v[232:235], v[2:17]
	ds_read_b128 v[232:235], v188 offset:63488
	v_max3_f32 v247, v247, v106, v107
	v_max3_f32 v247, v247, v108, v109
	v_add_u32_e32 v188, v197, v202
	v_cvt_pk_bf16_f32 v216, v114, v115
	v_cvt_pk_bf16_f32 v217, v116, v117
	v_cvt_pk_bf16_f32 v218, v118, v119
	v_cvt_pk_bf16_f32 v219, v120, v121
	s_waitcnt lgkmcnt(3)
	v_mfma_f32_32x32x16_bf16 v[50:65], v[216:219], v[220:223], v[50:65]
	ds_read_b128 v[220:223], v188 offset:51200
	v_max3_f32 v247, v247, v110, v111
	v_max3_f32 v249, v247, v112, v113
	s_waitcnt lgkmcnt(3)
	v_mfma_f32_32x32x16_bf16 v[34:49], v[216:219], v[224:227], v[34:49]
	ds_read_b128 v[224:227], v188 offset:55296
	s_waitcnt lgkmcnt(3)
	v_mfma_f32_32x32x16_bf16 v[18:33], v[216:219], v[228:231], v[18:33]
	ds_read_b128 v[228:231], v188 offset:59392
	s_waitcnt lgkmcnt(3)
	v_mfma_f32_32x32x16_bf16 v[2:17], v[216:219], v[232:235], v[2:17]
	ds_read_b128 v[232:235], v188 offset:63488
	v_cvt_pk_bf16_f32 v216, v122, v123
	v_cvt_pk_bf16_f32 v217, v124, v125
	v_cvt_pk_bf16_f32 v218, v126, v127
	v_cvt_pk_bf16_f32 v219, v128, v129
	v_mov_b32_e32 v188, v186
	s_waitcnt lgkmcnt(3)
	v_mfma_f32_32x32x16_bf16 v[50:65], v[216:219], v[220:223], v[50:65]
	s_waitcnt lgkmcnt(2)
	v_mfma_f32_32x32x16_bf16 v[34:49], v[216:219], v[224:227], v[34:49]
	s_waitcnt lgkmcnt(1)
	v_mfma_f32_32x32x16_bf16 v[18:33], v[216:219], v[228:231], v[18:33]
	s_waitcnt lgkmcnt(0)
	v_mfma_f32_32x32x16_bf16 v[2:17], v[216:219], v[232:235], v[2:17]
	s_or_b64 exec, exec, s[56:57]
	s_andn2_b64 vcc, exec, s[54:55]
	s_cbranch_vccnz .LBB0_1330
